# gu_strips (FFN1 gate|up int8 quantisation): first two K-tiles of every wave kept in registers between the absmax pass and the quantise pass (no re-read); on top of v022
# speedup vs baseline: 1.0106x; 1.0106x over previous
; __device__ __forceinline__ void gu_load(f32x4 (&v)[16], float& gA, float& gB, const GUDesc& d, int lane) {
;     const int kr = lane >> 3, nq = lane & 7;
;     const float* __restrict__ src = d.W + (size_t)(d.k0 + 4 * kr) * d.N + d.n0 + 4 * nq;
;     gA = d.gain ? d.gain[d.k0 + lane] : 1.0f; gB = d.gain ? d.gain[d.k0 + 64 + lane] : 1.0f;
; #pragma unroll
;     for (int i = 0; i < 16; ++i) v[i] = *(const f32x4*)(src + (size_t)(32 * (i >> 2) + (i & 3)) * d.N);
; }
; __device__ __forceinline__ void gu_strip(Frame& F, int uidx, int par) {
;     ...
;     for (int kt = F.wave; kt < nkt; kt += 8) {
;         f32x4 v[16]; float gA, gB; d.k0 = 128 * kt; gu_load(v, gA, gB, d, lane);
; #pragma unroll
;         for (int jq = 0; jq < 4; ++jq) {
; #pragma unroll
;             for (int e2 = 0; e2 < 4; ++e2) {
;                 const float g = jq < 2 ? __shfl(gA, 32 * jq + 4 * kr + e2) : __shfl(gB, 32 * (jq - 2) + 4 * kr + e2);
; #pragma unroll
;                 for (int e = 0; e < 4; ++e) cm[e] = fmaxf(cm[e], fabsf(v[4 * jq + e2][e] * g));
;             }
;         }
;     }
.LBB0_1082:
	v_mad_u64_u32 v[14:15], s[46:47], s16, v6, 0
	v_lshl_add_u64 v[26:27], v[14:15], 2, v[4:5]
	v_lshl_add_u64 v[30:31], v[26:27], 0, s[0:1]
	v_lshl_add_u64 v[34:35], v[30:31], 0, s[0:1]
	global_load_dwordx4 v[14:17], v[26:27], off
	s_waitcnt vmcnt(2)
	ds_bpermute_b32 v23, v41, v12
	global_load_dwordx4 v[26:29], v[30:31], off
	ds_bpermute_b32 v112, v42, v12
	global_load_dwordx4 v[30:33], v[34:35], off
	v_lshl_add_u64 v[34:35], v[34:35], 0, s[0:1]
	global_load_dwordx4 v[60:63], v[34:35], off
	v_lshl_add_u64 v[34:35], v[34:35], 0, s[18:19]
	global_load_dwordx4 v[64:67], v[34:35], off
	v_lshl_add_u64 v[34:35], v[34:35], 0, s[0:1]
	global_load_dwordx4 v[68:71], v[34:35], off
	v_lshl_add_u64 v[34:35], v[34:35], 0, s[0:1]
	global_load_dwordx4 v[72:75], v[34:35], off
	v_lshl_add_u64 v[34:35], v[34:35], 0, s[0:1]
	global_load_dwordx4 v[76:79], v[34:35], off
	v_lshl_add_u64 v[34:35], v[34:35], 0, s[18:19]
	global_load_dwordx4 v[80:83], v[34:35], off
	v_lshl_add_u64 v[34:35], v[34:35], 0, s[0:1]
	global_load_dwordx4 v[84:87], v[34:35], off
	v_lshl_add_u64 v[34:35], v[34:35], 0, s[0:1]
	global_load_dwordx4 v[88:91], v[34:35], off
	v_lshl_add_u64 v[34:35], v[34:35], 0, s[0:1]
	global_load_dwordx4 v[92:95], v[34:35], off
	ds_bpermute_b32 v113, v43, v12
	ds_bpermute_b32 v114, v44, v12
	ds_bpermute_b32 v115, v45, v12
	ds_bpermute_b32 v116, v46, v12
	ds_bpermute_b32 v117, v47, v12
	ds_bpermute_b32 v118, v48, v12
	v_lshl_add_u64 v[12:13], v[34:35], 0, s[18:19]
	global_load_dwordx4 v[96:99], v[12:13], off
	v_lshl_add_u64 v[12:13], v[12:13], 0, s[0:1]
	global_load_dwordx4 v[100:103], v[12:13], off
	v_lshl_add_u64 v[12:13], v[12:13], 0, s[0:1]
	global_load_dwordx4 v[104:107], v[12:13], off
	v_lshl_add_u64 v[12:13], v[12:13], 0, s[0:1]
	global_load_dwordx4 v[108:111], v[12:13], off
	s_waitcnt vmcnt(16)
	ds_bpermute_b32 v119, v41, v8
	s_add_i32 s17, s17, 8
	v_add_u32_e32 v6, 0x400, v6
	s_cmp_gt_u32 s17, 23
	v_add_u32_e32 v18, 0x400, v18
	s_waitcnt vmcnt(15) lgkmcnt(8)
	v_mov_b32_e32 v251, v14
	v_mov_b32_e32 v252, v15
	v_mov_b32_e32 v253, v16
	v_mov_b32_e32 v254, v17
	v_mul_f32_e32 v12, v14, v23
	v_mul_f32_e32 v14, v16, v23
	s_waitcnt vmcnt(14) lgkmcnt(7)
	v_mov_b32_e32 v255, v26
	v_mul_f32_e32 v16, v26, v112
	v_max3_f32 v10, v10, |v12|, |v16|
	s_waitcnt vmcnt(13) lgkmcnt(6)
	v_mul_f32_e32 v12, v30, v113
	v_mul_f32_e32 v13, v15, v23
	s_waitcnt vmcnt(12) lgkmcnt(5)
	v_mul_f32_e32 v16, v60, v114
	v_max3_f32 v10, v10, |v12|, |v16|
	s_waitcnt vmcnt(11) lgkmcnt(4)
	v_mul_f32_e32 v12, v64, v115
	v_mul_f32_e32 v15, v17, v23
	s_waitcnt vmcnt(10) lgkmcnt(3)
	v_mul_f32_e32 v16, v68, v116
	v_max3_f32 v10, v10, |v12|, |v16|
	s_waitcnt vmcnt(9) lgkmcnt(2)
	v_mul_f32_e32 v12, v72, v117
	v_mul_f32_e32 v17, v27, v112
	s_waitcnt vmcnt(8) lgkmcnt(1)
	v_mul_f32_e32 v16, v76, v118
	v_max3_f32 v10, v10, |v12|, |v16|
	ds_bpermute_b32 v12, v42, v8
	v_mul_f32_e32 v23, v28, v112
	v_max3_f32 v11, v11, |v13|, |v17|
	v_mul_f32_e32 v13, v31, v113
	v_mul_f32_e32 v17, v61, v114
	v_mul_f32_e32 v26, v29, v112
	v_max3_f32 v9, v9, |v14|, |v23|
	v_mul_f32_e32 v14, v32, v113
	v_mul_f32_e32 v23, v62, v114
	v_max3_f32 v11, v11, |v13|, |v17|
	v_mul_f32_e32 v13, v65, v115
	v_mul_f32_e32 v17, v69, v116
	v_max3_f32 v7, v7, |v15|, |v26|
	v_mul_f32_e32 v15, v33, v113
	v_mul_f32_e32 v26, v63, v114
	v_max3_f32 v9, v9, |v14|, |v23|
	v_mul_f32_e32 v14, v66, v115
	v_mul_f32_e32 v23, v70, v116
	v_max3_f32 v11, v11, |v13|, |v17|
	v_mul_f32_e32 v13, v73, v117
	v_mul_f32_e32 v17, v77, v118
	v_max3_f32 v7, v7, |v15|, |v26|
	v_mul_f32_e32 v15, v67, v115
	v_mul_f32_e32 v26, v71, v116
	v_max3_f32 v9, v9, |v14|, |v23|
	v_mul_f32_e32 v14, v74, v117
	v_mul_f32_e32 v23, v78, v118
	v_max3_f32 v11, v11, |v13|, |v17|
	s_waitcnt vmcnt(7) lgkmcnt(1)
	v_mul_f32_e32 v13, v80, v119
	s_waitcnt vmcnt(6) lgkmcnt(0)
	v_mul_f32_e32 v17, v84, v12
	v_max3_f32 v7, v7, |v15|, |v26|
	v_mul_f32_e32 v15, v75, v117
	v_mul_f32_e32 v26, v79, v118
	v_max3_f32 v9, v9, |v14|, |v23|
	v_mul_f32_e32 v14, v81, v119
	v_max3_f32 v10, v10, |v13|, |v17|
	v_mul_f32_e32 v13, v85, v12
	v_max3_f32 v7, v7, |v15|, |v26|
	v_mul_f32_e32 v16, v83, v119
	v_max3_f32 v11, v11, |v14|, |v13|
	v_mul_f32_e32 v13, v86, v12
	v_mul_f32_e32 v12, v87, v12
	ds_bpermute_b32 v14, v43, v8
	v_max3_f32 v7, v7, |v16|, |v12|
	ds_bpermute_b32 v12, v44, v8
	v_mul_f32_e32 v15, v82, v119
	v_max3_f32 v9, v9, |v15|, |v13|
	s_waitcnt vmcnt(5) lgkmcnt(1)
	v_mul_f32_e32 v13, v88, v14
	v_mul_f32_e32 v15, v89, v14
	s_waitcnt vmcnt(4) lgkmcnt(0)
	v_mul_f32_e32 v17, v92, v12
	v_max3_f32 v10, v10, |v13|, |v17|
	v_mul_f32_e32 v13, v93, v12
	v_mul_f32_e32 v16, v90, v14
	v_mul_f32_e32 v14, v91, v14
	v_max3_f32 v11, v11, |v15|, |v13|
	v_mul_f32_e32 v13, v94, v12
	v_mul_f32_e32 v12, v95, v12
	ds_bpermute_b32 v15, v45, v8
	v_max3_f32 v7, v7, |v14|, |v12|
	ds_bpermute_b32 v12, v46, v8
	v_max3_f32 v9, v9, |v16|, |v13|
	s_waitcnt vmcnt(3) lgkmcnt(1)
	v_mul_f32_e32 v13, v96, v15
	v_mul_f32_e32 v14, v97, v15
	s_waitcnt vmcnt(2) lgkmcnt(0)
	v_mul_f32_e32 v17, v100, v12
	v_max3_f32 v10, v10, |v13|, |v17|
	v_mul_f32_e32 v13, v101, v12
	v_max3_f32 v11, v11, |v14|, |v13|
	ds_bpermute_b32 v14, v47, v8
	ds_bpermute_b32 v8, v48, v8
	v_mul_f32_e32 v16, v98, v15
	v_mul_f32_e32 v15, v99, v15
	v_mul_f32_e32 v13, v102, v12
	v_mul_f32_e32 v12, v103, v12
	v_max3_f32 v9, v9, |v16|, |v13|
	v_max3_f32 v7, v7, |v15|, |v12|
	s_waitcnt vmcnt(1) lgkmcnt(1)
	v_mul_f32_e32 v12, v104, v14
	s_waitcnt vmcnt(0) lgkmcnt(0)
	v_mul_f32_e32 v16, v108, v8
	v_mul_f32_e32 v13, v105, v14
	v_max3_f32 v10, v10, |v12|, |v16|
	v_mul_f32_e32 v12, v109, v8
	v_mul_f32_e32 v15, v106, v14
	v_mul_f32_e32 v14, v107, v14
	v_max3_f32 v11, v11, |v13|, |v12|
	v_mul_f32_e32 v12, v110, v8
	v_mul_f32_e32 v8, v111, v8
	v_max3_f32 v9, v9, |v15|, |v12|
	v_max3_f32 v7, v7, |v14|, |v8|
	s_lshr_b32 s98, s17, 3
	s_cmp_eq_u32 s98, 0
	s_cbranch_scc1 .Lmy_sv0
	s_cmp_eq_u32 s98, 1
	s_cbranch_scc1 .Lmy_sv1
	s_branch .Lmy_sv_done
; __device__ __forceinline__ void gu_strip(Frame& F, int uidx, int par) {
;     ...
;     for (int kt = F.wave; kt < nkt; kt += 8) {
;         f32x4 v[16]; float gA, gB; d.k0 = 128 * kt; gu_load(v, gA, gB, d, lane);
; #pragma unroll
;         for (int jq = 0; jq < 4; ++jq) {
; #pragma unroll
;             for (int e2 = 0; e2 < 4; ++e2) {
;                 const float g = jq < 2 ? __shfl(gA, 32 * jq + 4 * kr + e2) : __shfl(gB, 32 * (jq - 2) + 4 * kr + e2);
; #pragma unroll
;                 for (int e = 0; e < 4; ++e) cm[e] = fmaxf(cm[e], fabsf(v[4 * jq + e2][e] * g));
;             }
;         }
;     }
; #pragma unroll
;     for (int e = 0; e < 4; ++e) { float m = cm[e]; m = fmaxf(m, __shfl_xor(m, 8)); m = fmaxf(m, __shfl_xor(m, 16)); m = fmaxf(m, __shfl_xor(m, 32)); cm[e] = m; }
;     if (kr == 0) { for (int e = 0; e < 4; ++e) part[F.wave * 32 + 4 * nq + e] = cm[e]; }
;     __syncthreads();
;     float inv[4];
; #pragma unroll
;     for (int e = 0; e < 4; ++e) {
;         float m = 0.f;
; #pragma unroll
;         for (int w = 0; w < 8; ++w) m = fmaxf(m, part[w * 32 + 4 * nq + e]);
;         inv[e] = m > 0.f ? 127.0f / m : 0.f;
;         if (F.wave == 0 && kr == 0) { const int n = d.n0 + 4 * nq + e; d.sb[d.il ? gu_dest(n, d.bj) : n] = m * (1.0f / 127.0f); }
;     }
;     for (int kt = F.wave; kt < nkt; kt += 8) {
;         f32x4 v[16]; float gA, gB; d.k0 = 128 * kt; gu_load(v, gA, gB, d, lane);
;         gu_finish_t<true, 0>(v, gA, gB, d, T, lane, inv);
;     }
.Lmy_sv0:
	v_mov_b32_e32 v122, v251
	v_mov_b32_e32 v123, v252
	v_mov_b32_e32 v124, v253
	v_mov_b32_e32 v125, v254
	v_mov_b32_e32 v126, v255
	v_mov_b32_e32 v127, v27
	v_mov_b32_e32 v128, v28
	v_mov_b32_e32 v129, v29
	v_mov_b32_e32 v130, v30
	v_mov_b32_e32 v131, v31
	v_mov_b32_e32 v132, v32
	v_mov_b32_e32 v133, v33
	v_mov_b32_e32 v134, v60
	v_mov_b32_e32 v135, v61
	v_mov_b32_e32 v136, v62
	v_mov_b32_e32 v137, v63
	v_mov_b32_e32 v138, v64
	v_mov_b32_e32 v139, v65
	v_mov_b32_e32 v140, v66
	v_mov_b32_e32 v141, v67
	v_mov_b32_e32 v142, v68
	v_mov_b32_e32 v143, v69
	v_mov_b32_e32 v144, v70
	v_mov_b32_e32 v145, v71
	v_mov_b32_e32 v146, v72
	v_mov_b32_e32 v147, v73
	v_mov_b32_e32 v148, v74
	v_mov_b32_e32 v149, v75
	v_mov_b32_e32 v150, v76
	v_mov_b32_e32 v151, v77
	v_mov_b32_e32 v152, v78
	v_mov_b32_e32 v153, v79
	v_mov_b32_e32 v154, v80
	v_mov_b32_e32 v155, v81
	v_mov_b32_e32 v156, v82
	v_mov_b32_e32 v157, v83
	v_mov_b32_e32 v158, v84
	v_mov_b32_e32 v159, v85
	v_mov_b32_e32 v160, v86
	v_mov_b32_e32 v161, v87
	v_mov_b32_e32 v162, v88
	v_mov_b32_e32 v163, v89
	v_mov_b32_e32 v164, v90
	v_mov_b32_e32 v165, v91
	v_mov_b32_e32 v166, v92
	v_mov_b32_e32 v167, v93
	v_mov_b32_e32 v168, v94
	v_mov_b32_e32 v169, v95
	v_mov_b32_e32 v170, v96
	v_mov_b32_e32 v171, v97
	v_mov_b32_e32 v172, v98
	v_mov_b32_e32 v173, v99
	v_mov_b32_e32 v174, v100
	v_mov_b32_e32 v175, v101
	v_mov_b32_e32 v176, v102
	v_mov_b32_e32 v177, v103
	v_mov_b32_e32 v178, v104
	v_mov_b32_e32 v179, v105
	v_mov_b32_e32 v180, v106
	v_mov_b32_e32 v181, v107
	v_mov_b32_e32 v182, v108
	v_mov_b32_e32 v183, v109
	v_mov_b32_e32 v184, v110
	v_mov_b32_e32 v185, v111
	s_branch .Lmy_sv_done
.Lmy_sv1:
	v_mov_b32_e32 v186, v251
	v_mov_b32_e32 v187, v252
	v_mov_b32_e32 v188, v253
	v_mov_b32_e32 v189, v254
	v_mov_b32_e32 v190, v255
	v_mov_b32_e32 v191, v27
	v_mov_b32_e32 v192, v28
	v_mov_b32_e32 v193, v29
	v_mov_b32_e32 v194, v30
	v_mov_b32_e32 v195, v31
	v_mov_b32_e32 v196, v32
	v_mov_b32_e32 v197, v33
	v_mov_b32_e32 v198, v60
	v_mov_b32_e32 v199, v61
	v_mov_b32_e32 v200, v62
	v_mov_b32_e32 v201, v63
	v_mov_b32_e32 v202, v64
	v_mov_b32_e32 v203, v65
	v_mov_b32_e32 v204, v66
	v_mov_b32_e32 v205, v67
	v_mov_b32_e32 v206, v68
	v_mov_b32_e32 v207, v69
	v_mov_b32_e32 v208, v70
	v_mov_b32_e32 v209, v71
	v_mov_b32_e32 v210, v72
	v_mov_b32_e32 v211, v73
	v_mov_b32_e32 v212, v74
	v_mov_b32_e32 v213, v75
	v_mov_b32_e32 v214, v76
	v_mov_b32_e32 v215, v77
	v_mov_b32_e32 v216, v78
	v_mov_b32_e32 v217, v79
	v_mov_b32_e32 v218, v80
	v_mov_b32_e32 v219, v81
	v_mov_b32_e32 v220, v82
	v_mov_b32_e32 v221, v83
	v_mov_b32_e32 v222, v84
	v_mov_b32_e32 v223, v85
	v_mov_b32_e32 v224, v86
	v_mov_b32_e32 v225, v87
	v_mov_b32_e32 v226, v88
	v_mov_b32_e32 v227, v89
	v_mov_b32_e32 v228, v90
	v_mov_b32_e32 v229, v91
	v_mov_b32_e32 v230, v92
	v_mov_b32_e32 v231, v93
	v_mov_b32_e32 v232, v94
	v_mov_b32_e32 v233, v95
	v_mov_b32_e32 v234, v96
	v_mov_b32_e32 v235, v97
	v_mov_b32_e32 v236, v98
	v_mov_b32_e32 v237, v99
	v_mov_b32_e32 v238, v100
	v_mov_b32_e32 v239, v101
	v_mov_b32_e32 v240, v102
	v_mov_b32_e32 v241, v103
	v_mov_b32_e32 v242, v104
	v_mov_b32_e32 v243, v105
	v_mov_b32_e32 v244, v106
	v_mov_b32_e32 v245, v107
	v_mov_b32_e32 v247, v108
	v_mov_b32_e32 v248, v109
	v_mov_b32_e32 v249, v110
	v_mov_b32_e32 v250, v111
.Lmy_sv_done:
	s_cmp_gt_u32 s17, 23
	s_cbranch_scc1 .LBB0_1085

; __device__ __forceinline__ void gu_load(f32x4 (&v)[16], float& gA, float& gB, const GUDesc& d, int lane) {
;     const int kr = lane >> 3, nq = lane & 7;
;     const float* __restrict__ src = d.W + (size_t)(d.k0 + 4 * kr) * d.N + d.n0 + 4 * nq;
;     gA = d.gain ? d.gain[d.k0 + lane] : 1.0f; gB = d.gain ? d.gain[d.k0 + 64 + lane] : 1.0f;
; #pragma unroll
;     for (int i = 0; i < 16; ++i) v[i] = *(const f32x4*)(src + (size_t)(32 * (i >> 2) + (i & 3)) * d.N);
; }
; __device__ __forceinline__ void gu_strip(Frame& F, int uidx, int par) {
;     ...
;     for (int kt = F.wave; kt < nkt; kt += 8) {
;         f32x4 v[16]; float gA, gB; d.k0 = 128 * kt; gu_load(v, gA, gB, d, lane);
;         gu_finish_t<true, 0>(v, gA, gB, d, T, lane, inv);
;     }
.LBB0_1098:
	s_lshr_b32 s98, s6, 3
	s_cmp_lt_u32 s98, 2
	s_cbranch_scc0 .Lmy_pb_load
	s_cmp_eq_u32 s98, 0
	s_cbranch_scc0 .Lmy_pb_r1
	v_mov_b32_e32 v70, v122
	v_mov_b32_e32 v71, v123
	v_mov_b32_e32 v72, v124
	v_mov_b32_e32 v73, v125
	v_mov_b32_e32 v74, v126
	v_mov_b32_e32 v75, v127
	v_mov_b32_e32 v76, v128
	v_mov_b32_e32 v77, v129
	v_mov_b32_e32 v78, v130
	v_mov_b32_e32 v79, v131
	v_mov_b32_e32 v80, v132
	v_mov_b32_e32 v81, v133
	v_mov_b32_e32 v82, v134
	v_mov_b32_e32 v83, v135
	v_mov_b32_e32 v84, v136
	v_mov_b32_e32 v85, v137
	v_mov_b32_e32 v86, v138
	v_mov_b32_e32 v87, v139
	v_mov_b32_e32 v88, v140
	v_mov_b32_e32 v89, v141
	v_mov_b32_e32 v90, v142
	v_mov_b32_e32 v91, v143
	v_mov_b32_e32 v92, v144
	v_mov_b32_e32 v93, v145
	v_mov_b32_e32 v94, v146
	v_mov_b32_e32 v95, v147
	v_mov_b32_e32 v96, v148
	v_mov_b32_e32 v97, v149
	v_mov_b32_e32 v98, v150
	v_mov_b32_e32 v99, v151
	v_mov_b32_e32 v100, v152
	v_mov_b32_e32 v101, v153
	v_mov_b32_e32 v102, v154
	v_mov_b32_e32 v103, v155
	v_mov_b32_e32 v104, v156
	v_mov_b32_e32 v105, v157
	v_mov_b32_e32 v106, v158
	v_mov_b32_e32 v107, v159
	v_mov_b32_e32 v108, v160
	v_mov_b32_e32 v109, v161
	v_mov_b32_e32 v110, v162
	v_mov_b32_e32 v111, v163
	v_mov_b32_e32 v112, v164
	v_mov_b32_e32 v113, v165
	v_mov_b32_e32 v114, v166
	v_mov_b32_e32 v115, v167
	v_mov_b32_e32 v116, v168
	v_mov_b32_e32 v117, v169
	v_mov_b32_e32 v2, v170
	v_mov_b32_e32 v3, v171
	v_mov_b32_e32 v4, v172
	v_mov_b32_e32 v5, v173
	v_mov_b32_e32 v6, v174
	v_mov_b32_e32 v7, v175
	v_mov_b32_e32 v8, v176
	v_mov_b32_e32 v9, v177
	v_mov_b32_e32 v10, v178
	v_mov_b32_e32 v11, v179
	v_mov_b32_e32 v12, v180
	v_mov_b32_e32 v13, v181
	v_mov_b32_e32 v14, v182
	v_mov_b32_e32 v15, v183
	v_mov_b32_e32 v16, v184
	v_mov_b32_e32 v17, v185
	s_waitcnt vmcnt(0)
	s_branch .Lmy_pb_after
.Lmy_pb_r1:
	v_mov_b32_e32 v70, v186
	v_mov_b32_e32 v71, v187
	v_mov_b32_e32 v72, v188
	v_mov_b32_e32 v73, v189
	v_mov_b32_e32 v74, v190
	v_mov_b32_e32 v75, v191
	v_mov_b32_e32 v76, v192
	v_mov_b32_e32 v77, v193
	v_mov_b32_e32 v78, v194
	v_mov_b32_e32 v79, v195
	v_mov_b32_e32 v80, v196
	v_mov_b32_e32 v81, v197
	v_mov_b32_e32 v82, v198
	v_mov_b32_e32 v83, v199
	v_mov_b32_e32 v84, v200
	v_mov_b32_e32 v85, v201
	v_mov_b32_e32 v86, v202
	v_mov_b32_e32 v87, v203
	v_mov_b32_e32 v88, v204
	v_mov_b32_e32 v89, v205
	v_mov_b32_e32 v90, v206
	v_mov_b32_e32 v91, v207
	v_mov_b32_e32 v92, v208
	v_mov_b32_e32 v93, v209
	v_mov_b32_e32 v94, v210
	v_mov_b32_e32 v95, v211
	v_mov_b32_e32 v96, v212
	v_mov_b32_e32 v97, v213
	v_mov_b32_e32 v98, v214
	v_mov_b32_e32 v99, v215
	v_mov_b32_e32 v100, v216
	v_mov_b32_e32 v101, v217
	v_mov_b32_e32 v102, v218
	v_mov_b32_e32 v103, v219
	v_mov_b32_e32 v104, v220
	v_mov_b32_e32 v105, v221
	v_mov_b32_e32 v106, v222
	v_mov_b32_e32 v107, v223
	v_mov_b32_e32 v108, v224
	v_mov_b32_e32 v109, v225
	v_mov_b32_e32 v110, v226
	v_mov_b32_e32 v111, v227
	v_mov_b32_e32 v112, v228
	v_mov_b32_e32 v113, v229
	v_mov_b32_e32 v114, v230
	v_mov_b32_e32 v115, v231
	v_mov_b32_e32 v116, v232
	v_mov_b32_e32 v117, v233
	v_mov_b32_e32 v2, v234
	v_mov_b32_e32 v3, v235
	v_mov_b32_e32 v4, v236
	v_mov_b32_e32 v5, v237
	v_mov_b32_e32 v6, v238
	v_mov_b32_e32 v7, v239
	v_mov_b32_e32 v8, v240
	v_mov_b32_e32 v9, v241
	v_mov_b32_e32 v10, v242
	v_mov_b32_e32 v11, v243
	v_mov_b32_e32 v12, v244
	v_mov_b32_e32 v13, v245
	v_mov_b32_e32 v14, v247
	v_mov_b32_e32 v15, v248
	v_mov_b32_e32 v16, v249
	v_mov_b32_e32 v17, v250
	s_waitcnt vmcnt(0)
	s_branch .Lmy_pb_after

; __device__ __forceinline__ unsigned pack4_i8(float a, float b, float c, float d) {
;     unsigned w = __builtin_amdgcn_cvt_pk_u8_f32(a + 128.0f, 0u, 0u); w = __builtin_amdgcn_cvt_pk_u8_f32(b + 128.0f, 1u, w); w = __builtin_amdgcn_cvt_pk_u8_f32(c + 128.0f, 2u, w); w = __builtin_amdgcn_cvt_pk_u8_f32(d + 128.0f, 3u, w);
;     return w ^ 0x80808080u;
; }
; template <bool STRIP, int ROT>
; __device__ __forceinline__ void gu_finish_t(f32x4 (&v)[16], float gA, float gB, const GUDesc& d, LAS unsigned* T, int lane, const float (&sinv)[4]) {
;     ...
;     for (int jq = 0; jq < 4; ++jq) {
;         float g[4];
; #pragma unroll
;         for (int e2 = 0; e2 < 4; ++e2) g[e2] = jq < 2 ? __shfl(gA, 32 * jq + 4 * kr + e2) : __shfl(gB, 32 * (jq - 2) + 4 * kr + e2);
; #pragma unroll
;         for (int e = 0; e < 4; ++e)
;             T[(4 * nq + e) * 33 + 8 * jq + kr] = pack4_i8(v[4 * jq + 0][e] * g[0] * inv[e], v[4 * jq + 1][e] * g[1] * inv[e], v[4 * jq + 2][e] * g[2] * inv[e], v[4 * jq + 3][e] * g[3] * inv[e]);
;     }
.Lmy_pb_after:
	s_waitcnt vmcnt(17)
	ds_bpermute_b32 v118, v41, v69
	ds_bpermute_b32 v119, v42, v69
	ds_bpermute_b32 v120, v43, v69
	ds_bpermute_b32 v121, v44, v69
	s_add_i32 s7, s6, 8
	v_add_u32_e32 v67, 0x400, v67
	v_add_u32_e32 v18, 0x400, v18
	s_cmp_lt_u32 s6, 24
	s_waitcnt vmcnt(15) lgkmcnt(3)
	v_mul_f32_e32 v70, v70, v118
	v_mul_f32_e32 v71, v71, v118
	s_waitcnt vmcnt(14) lgkmcnt(2)
	v_mul_f32_e32 v74, v74, v119
	v_fmaak_f32 v70, v63, v70, 0x43000000
	v_mul_f32_e32 v72, v72, v118
	v_mul_f32_e32 v75, v75, v119
	v_fmaak_f32 v71, v62, v71, 0x43000000
	s_waitcnt vmcnt(13) lgkmcnt(1)
	v_mul_f32_e32 v78, v78, v120
	v_cvt_pk_u8_f32 v70, v70, 0, 0
	v_fmaak_f32 v74, v63, v74, 0x43000000
	v_mul_f32_e32 v76, v76, v119
	v_fmaak_f32 v72, v61, v72, 0x43000000
	v_mul_f32_e32 v79, v79, v120
	v_cvt_pk_u8_f32 v71, v71, 0, 0
	v_fmaak_f32 v75, v62, v75, 0x43000000
	s_waitcnt vmcnt(12) lgkmcnt(0)
	v_mul_f32_e32 v82, v82, v121
	v_cvt_pk_u8_f32 v70, v74, 1, v70
	v_fmaak_f32 v74, v63, v78, 0x43000000
	v_mul_f32_e32 v80, v80, v120
	v_cvt_pk_u8_f32 v72, v72, 0, 0
	v_fmaak_f32 v76, v61, v76, 0x43000000
	v_mul_f32_e32 v78, v83, v121
	v_cvt_pk_u8_f32 v71, v75, 1, v71
	v_fmaak_f32 v75, v62, v79, 0x43000000
	v_cvt_pk_u8_f32 v70, v74, 2, v70
	v_fmaak_f32 v74, v63, v82, 0x43000000
	v_mul_f32_e32 v73, v73, v118
	v_mul_f32_e32 v79, v84, v121
	v_cvt_pk_u8_f32 v72, v76, 1, v72
	v_fmaak_f32 v76, v61, v80, 0x43000000
	v_cvt_pk_u8_f32 v71, v75, 2, v71
	v_fmaak_f32 v75, v62, v78, 0x43000000
	v_cvt_pk_u8_f32 v70, v74, 3, v70
	ds_bpermute_b32 v74, v45, v69
	v_mul_f32_e32 v77, v77, v119
	v_fmaak_f32 v73, v60, v73, 0x43000000
	v_cvt_pk_u8_f32 v72, v76, 2, v72
	v_fmaak_f32 v76, v61, v79, 0x43000000
	v_cvt_pk_u8_f32 v71, v75, 3, v71
	ds_bpermute_b32 v75, v46, v69
	v_mul_f32_e32 v81, v81, v120
	v_cvt_pk_u8_f32 v73, v73, 0, 0
	v_fmaak_f32 v77, v60, v77, 0x43000000
	v_cvt_pk_u8_f32 v72, v76, 3, v72
	ds_bpermute_b32 v76, v47, v69
	v_mul_f32_e32 v80, v85, v121
	v_cvt_pk_u8_f32 v73, v77, 1, v73
	v_fmaak_f32 v77, v60, v81, 0x43000000
	ds_bpermute_b32 v69, v48, v69
	v_cvt_pk_u8_f32 v73, v77, 2, v73
	v_fmaak_f32 v77, v60, v80, 0x43000000
	v_cvt_pk_u8_f32 v73, v77, 3, v73
	s_waitcnt vmcnt(11) lgkmcnt(3)
	v_mul_f32_e32 v77, v86, v74
	s_waitcnt vmcnt(10) lgkmcnt(2)
	v_mul_f32_e32 v78, v90, v75
	v_fmaak_f32 v77, v63, v77, 0x43000000
	s_waitcnt vmcnt(9) lgkmcnt(1)
	v_mul_f32_e32 v79, v94, v76
	v_cvt_pk_u8_f32 v77, v77, 0, 0
	v_fmaak_f32 v78, v63, v78, 0x43000000
	s_waitcnt vmcnt(8) lgkmcnt(0)
	v_mul_f32_e32 v80, v98, v69
	v_cvt_pk_u8_f32 v77, v78, 1, v77
	v_fmaak_f32 v78, v63, v79, 0x43000000
	v_cvt_pk_u8_f32 v77, v78, 2, v77
	v_fmaak_f32 v78, v63, v80, 0x43000000
	v_cvt_pk_u8_f32 v77, v78, 3, v77
	v_xor_b32_e32 v70, 0x80808080, v70
	v_xor_b32_e32 v77, 0x80808080, v77
	ds_write2_b32 v54, v70, v77 offset1:8
	v_mul_f32_e32 v70, v87, v74
	v_mul_f32_e32 v77, v91, v75
	v_fmaak_f32 v70, v62, v70, 0x43000000
	v_mul_f32_e32 v78, v95, v76
	v_cvt_pk_u8_f32 v70, v70, 0, 0
	v_fmaak_f32 v77, v62, v77, 0x43000000
	v_mul_f32_e32 v79, v99, v69
	v_cvt_pk_u8_f32 v70, v77, 1, v70
	v_fmaak_f32 v77, v62, v78, 0x43000000
	v_cvt_pk_u8_f32 v70, v77, 2, v70
	v_fmaak_f32 v77, v62, v79, 0x43000000
	v_cvt_pk_u8_f32 v70, v77, 3, v70
	v_xor_b32_e32 v71, 0x80808080, v71
	v_xor_b32_e32 v70, 0x80808080, v70
	ds_write2_b32 v54, v71, v70 offset0:33 offset1:41
	v_mul_f32_e32 v70, v88, v74
	v_mul_f32_e32 v71, v92, v75
	v_fmaak_f32 v70, v61, v70, 0x43000000
	v_mul_f32_e32 v77, v96, v76
	v_cvt_pk_u8_f32 v70, v70, 0, 0
	v_fmaak_f32 v71, v61, v71, 0x43000000
	v_mul_f32_e32 v78, v100, v69
	v_cvt_pk_u8_f32 v70, v71, 1, v70
	v_fmaak_f32 v71, v61, v77, 0x43000000
	v_cvt_pk_u8_f32 v70, v71, 2, v70
	v_fmaak_f32 v71, v61, v78, 0x43000000
	v_cvt_pk_u8_f32 v70, v71, 3, v70
	v_xor_b32_e32 v72, 0x80808080, v72
	v_xor_b32_e32 v70, 0x80808080, v70
	ds_write2_b32 v54, v72, v70 offset0:66 offset1:74
	v_mul_f32_e32 v70, v89, v74
	v_mul_f32_e32 v71, v93, v75
	v_fmaak_f32 v70, v60, v70, 0x43000000
	v_mul_f32_e32 v72, v97, v76
	v_cvt_pk_u8_f32 v70, v70, 0, 0
	v_fmaak_f32 v71, v60, v71, 0x43000000
	v_mul_f32_e32 v69, v101, v69
	v_cvt_pk_u8_f32 v70, v71, 1, v70
	v_fmaak_f32 v71, v60, v72, 0x43000000
	v_cvt_pk_u8_f32 v70, v71, 2, v70
	v_fmaak_f32 v69, v60, v69, 0x43000000
	v_cvt_pk_u8_f32 v69, v69, 3, v70
	ds_bpermute_b32 v70, v41, v68
	ds_bpermute_b32 v71, v42, v68
	ds_bpermute_b32 v72, v43, v68
	ds_bpermute_b32 v74, v44, v68
	v_xor_b32_e32 v73, 0x80808080, v73
	v_xor_b32_e32 v69, 0x80808080, v69
	ds_write2_b32 v54, v73, v69 offset0:99 offset1:107
	s_waitcnt vmcnt(7) lgkmcnt(4)
	v_mul_f32_e32 v69, v102, v70
	s_waitcnt vmcnt(6) lgkmcnt(3)
	v_mul_f32_e32 v73, v106, v71
	v_fmaak_f32 v69, v63, v69, 0x43000000
	s_waitcnt vmcnt(5) lgkmcnt(2)
	v_mul_f32_e32 v75, v110, v72
	v_cvt_pk_u8_f32 v69, v69, 0, 0
	v_fmaak_f32 v73, v63, v73, 0x43000000
	s_waitcnt vmcnt(4) lgkmcnt(1)
; #define LAS __attribute__((address_space(3)))
; __host__ __device__ __forceinline__ size_t blk8_off(int r, int k, int KT8_) { return ((size_t)((r >> 8) * KT8_ + (k >> 7)) * 256 + (size_t)(r & 255)) * 128 + (size_t)(k & 127); }
; #define LDS_WAIT() asm volatile("s_waitcnt lgkmcnt(0)" ::: "memory")
; template <bool STRIP, int ROT>
; __device__ __forceinline__ void gu_finish_t(f32x4 (&v)[16], float gA, float gB, const GUDesc& d, LAS unsigned* T, int lane, const float (&sinv)[4]) {
;     ...
;     for (int jq = 0; jq < 4; ++jq) {
;         float g[4];
; #pragma unroll
;         for (int e2 = 0; e2 < 4; ++e2) g[e2] = jq < 2 ? __shfl(gA, 32 * jq + 4 * kr + e2) : __shfl(gB, 32 * (jq - 2) + 4 * kr + e2);
; #pragma unroll
;         for (int e = 0; e < 4; ++e)
;             T[(4 * nq + e) * 33 + 8 * jq + kr] = pack4_i8(v[4 * jq + 0][e] * g[0] * inv[e], v[4 * jq + 1][e] * g[1] * inv[e], v[4 * jq + 2][e] * g[2] * inv[e], v[4 * jq + 3][e] * g[3] * inv[e]);
;     }
;     LDS_WAIT(); asm volatile("" ::: "memory");
;     const int nl = lane >> 3, c = lane & 7;
; #pragma unroll
;     for (int g4 = 0; g4 < 4; ++g4) {
;         const int nloc = 8 * g4 + nl, dr = d.il ? gu_dest(d.n0 + nloc, d.bj) : d.n0 + nloc;
;         const LAS unsigned* t = T + nloc * 33 + 4 * c;
;         u32x4 o; o.x = t[0]; o.y = t[1]; o.z = t[2]; o.w = t[3];
;         *(u32x4*)(d.WQ + blk8_off(dr, d.k0 + 16 * c, d.kt8)) = o;
;         if (!STRIP) if (d.k0 == 0 && c == 0) d.sb[dr] = __uint_as_float(d.cmax[dr]) * (1.0f / 127.0f);
;     }
;     LDS_WAIT(); asm volatile("" ::: "memory");
	v_mul_f32_e32 v76, v114, v74
	v_cvt_pk_u8_f32 v69, v73, 1, v69
	v_fmaak_f32 v73, v63, v75, 0x43000000
	v_cvt_pk_u8_f32 v69, v73, 2, v69
	v_fmaak_f32 v73, v63, v76, 0x43000000
	v_cvt_pk_u8_f32 v69, v73, 3, v69
	v_mul_f32_e32 v73, v103, v70
	v_mul_f32_e32 v75, v107, v71
	v_fmaak_f32 v73, v62, v73, 0x43000000
	v_mul_f32_e32 v76, v111, v72
	v_cvt_pk_u8_f32 v73, v73, 0, 0
	v_fmaak_f32 v75, v62, v75, 0x43000000
	v_mul_f32_e32 v77, v115, v74
	v_cvt_pk_u8_f32 v73, v75, 1, v73
	v_fmaak_f32 v75, v62, v76, 0x43000000
	v_cvt_pk_u8_f32 v73, v75, 2, v73
	v_fmaak_f32 v75, v62, v77, 0x43000000
	v_cvt_pk_u8_f32 v73, v75, 3, v73
	v_mul_f32_e32 v75, v104, v70
	v_mul_f32_e32 v70, v105, v70
	v_mul_f32_e32 v76, v108, v71
	v_mul_f32_e32 v71, v109, v71
	v_fmaak_f32 v70, v60, v70, 0x43000000
	v_mul_f32_e32 v77, v112, v72
	v_mul_f32_e32 v72, v113, v72
	v_cvt_pk_u8_f32 v70, v70, 0, 0
	v_fmaak_f32 v71, v60, v71, 0x43000000
	v_mul_f32_e32 v78, v116, v74
	v_mul_f32_e32 v74, v117, v74
	v_cvt_pk_u8_f32 v70, v71, 1, v70
	v_fmaak_f32 v71, v60, v72, 0x43000000
	v_cvt_pk_u8_f32 v70, v71, 2, v70
	v_fmaak_f32 v71, v60, v74, 0x43000000
	v_cvt_pk_u8_f32 v70, v71, 3, v70
	ds_bpermute_b32 v71, v45, v68
	ds_bpermute_b32 v72, v46, v68
	ds_bpermute_b32 v74, v47, v68
	ds_bpermute_b32 v68, v48, v68
	v_xor_b32_e32 v69, 0x80808080, v69
	s_waitcnt vmcnt(3) lgkmcnt(3)
	v_mul_f32_e32 v2, v2, v71
	s_waitcnt vmcnt(2) lgkmcnt(2)
	v_mul_f32_e32 v6, v6, v72
	v_fmaak_f32 v2, v63, v2, 0x43000000
	s_waitcnt vmcnt(1) lgkmcnt(1)
	v_mul_f32_e32 v10, v10, v74
	v_cvt_pk_u8_f32 v2, v2, 0, 0
	v_fmaak_f32 v6, v63, v6, 0x43000000
	s_waitcnt vmcnt(0) lgkmcnt(0)
	v_mul_f32_e32 v14, v14, v68
	v_cvt_pk_u8_f32 v2, v6, 1, v2
	v_fmaak_f32 v6, v63, v10, 0x43000000
	v_cvt_pk_u8_f32 v2, v6, 2, v2
	v_fmaak_f32 v6, v63, v14, 0x43000000
	v_cvt_pk_u8_f32 v2, v6, 3, v2
	v_xor_b32_e32 v2, 0x80808080, v2
	ds_write2_b32 v54, v69, v2 offset0:16 offset1:24
	v_mul_f32_e32 v2, v3, v71
	v_mul_f32_e32 v3, v7, v72
	v_fmaak_f32 v2, v62, v2, 0x43000000
	v_mul_f32_e32 v6, v11, v74
	v_cvt_pk_u8_f32 v2, v2, 0, 0
	v_fmaak_f32 v3, v62, v3, 0x43000000
	v_mul_f32_e32 v7, v15, v68
	v_cvt_pk_u8_f32 v2, v3, 1, v2
	v_fmaak_f32 v3, v62, v6, 0x43000000
	v_cvt_pk_u8_f32 v2, v3, 2, v2
	v_fmaak_f32 v3, v62, v7, 0x43000000
	v_cvt_pk_u8_f32 v2, v3, 3, v2
	v_xor_b32_e32 v73, 0x80808080, v73
	v_xor_b32_e32 v2, 0x80808080, v2
	ds_write2_b32 v54, v73, v2 offset0:49 offset1:57
	v_mul_f32_e32 v2, v4, v71
	v_fmaak_f32 v75, v61, v75, 0x43000000
	v_mul_f32_e32 v3, v8, v72
	v_fmaak_f32 v2, v61, v2, 0x43000000
	v_cvt_pk_u8_f32 v75, v75, 0, 0
	v_fmaak_f32 v76, v61, v76, 0x43000000
	v_mul_f32_e32 v4, v12, v74
	v_cvt_pk_u8_f32 v2, v2, 0, 0
	v_fmaak_f32 v3, v61, v3, 0x43000000
	v_cvt_pk_u8_f32 v75, v76, 1, v75
	v_fmaak_f32 v76, v61, v77, 0x43000000
	v_mul_f32_e32 v6, v16, v68
	v_cvt_pk_u8_f32 v2, v3, 1, v2
	v_fmaak_f32 v3, v61, v4, 0x43000000
	v_cvt_pk_u8_f32 v75, v76, 2, v75
	v_fmaak_f32 v76, v61, v78, 0x43000000
	v_cvt_pk_u8_f32 v2, v3, 2, v2
	v_fmaak_f32 v3, v61, v6, 0x43000000
	v_cvt_pk_u8_f32 v75, v76, 3, v75
	v_cvt_pk_u8_f32 v2, v3, 3, v2
	v_xor_b32_e32 v75, 0x80808080, v75
	v_xor_b32_e32 v2, 0x80808080, v2
	ds_write2_b32 v54, v75, v2 offset0:82 offset1:90
	v_mul_f32_e32 v2, v5, v71
	v_mul_f32_e32 v3, v9, v72
	v_fmaak_f32 v2, v60, v2, 0x43000000
	v_mul_f32_e32 v4, v13, v74
	v_cvt_pk_u8_f32 v2, v2, 0, 0
	v_fmaak_f32 v3, v60, v3, 0x43000000
	v_mul_f32_e32 v5, v17, v68
	v_cvt_pk_u8_f32 v2, v3, 1, v2
	v_fmaak_f32 v3, v60, v4, 0x43000000
	v_cvt_pk_u8_f32 v2, v3, 2, v2
	v_fmaak_f32 v3, v60, v5, 0x43000000
	v_cvt_pk_u8_f32 v2, v3, 3, v2
	v_xor_b32_e32 v70, 0x80808080, v70
	v_xor_b32_e32 v2, 0x80808080, v2
	ds_write2_b32 v54, v70, v2 offset0:115 offset1:123
	s_waitcnt lgkmcnt(0)
	ds_read2_b32 v[2:3], v55 offset1:1
	ds_read2_b32 v[4:5], v55 offset0:2 offset1:3
	v_add_u32_e32 v6, s6, v23
	v_ashrrev_i32_e32 v7, 31, v6
	v_lshlrev_b64 v[6:7], 15, v[6:7]
	v_lshl_add_u64 v[10:11], v[28:29], 0, v[6:7]
	v_add_u32_e32 v6, 0x420, v55
	v_add_u32_e32 v8, 0x428, v55
	ds_read2_b32 v[6:7], v6 offset1:1
	ds_read2_b32 v[8:9], v8 offset1:1
	s_waitcnt lgkmcnt(2)
	global_store_dwordx4 v[10:11], v[2:5], off
	s_nop 1
	v_add_u32_e32 v2, s6, v64
	v_ashrrev_i32_e32 v3, 31, v2
	v_lshlrev_b64 v[2:3], 15, v[2:3]
	v_lshl_add_u64 v[2:3], v[30:31], 0, v[2:3]
	s_waitcnt lgkmcnt(0)
	global_store_dwordx4 v[2:3], v[6:9], off
	v_add_u32_e32 v2, 0x840, v55
	v_add_u32_e32 v4, 0x848, v55
	ds_read2_b32 v[2:3], v2 offset1:1
	ds_read2_b32 v[4:5], v4 offset1:1
	v_add_u32_e32 v6, s6, v65
	v_ashrrev_i32_e32 v7, 31, v6
	v_lshlrev_b64 v[6:7], 15, v[6:7]
	v_lshl_add_u64 v[10:11], v[32:33], 0, v[6:7]
	v_add_u32_e32 v6, 0xc60, v55
	v_add_u32_e32 v8, 0xc68, v55
	ds_read2_b32 v[6:7], v6 offset1:1
	ds_read2_b32 v[8:9], v8 offset1:1
	s_waitcnt lgkmcnt(2)
	global_store_dwordx4 v[10:11], v[2:5], off
	s_nop 1
	v_add_u32_e32 v2, s6, v66
	v_ashrrev_i32_e32 v3, 31, v2
	v_lshlrev_b64 v[2:3], 15, v[2:3]
	v_lshl_add_u64 v[2:3], v[34:35], 0, v[2:3]
	s_waitcnt lgkmcnt(0)
	global_store_dwordx4 v[2:3], v[6:9], off
	s_waitcnt lgkmcnt(0)
	s_mov_b32 s6, s7
	s_cbranch_scc0 .LBB0_1073

; __global__ void __launch_bounds__(512, 2) mk_fwd(Args args) {
	.amdhsa_kernel _Z6mk_fwd4Args
		.amdhsa_group_segment_fixed_size 0
		.amdhsa_private_segment_fixed_size 0
		.amdhsa_kernarg_size 464
		.amdhsa_user_sgpr_count 2
		.amdhsa_user_sgpr_dispatch_ptr 0
		.amdhsa_user_sgpr_queue_ptr 0
		.amdhsa_user_sgpr_kernarg_segment_ptr 1
		.amdhsa_user_sgpr_dispatch_id 0
		.amdhsa_user_sgpr_kernarg_preload_length 0
		.amdhsa_user_sgpr_kernarg_preload_offset 0
		.amdhsa_user_sgpr_private_segment_size 0
		.amdhsa_uses_dynamic_stack 0
		.amdhsa_enable_private_segment 0
		.amdhsa_system_sgpr_workgroup_id_x 1
		.amdhsa_system_sgpr_workgroup_id_y 0
		.amdhsa_system_sgpr_workgroup_id_z 0
		.amdhsa_system_sgpr_workgroup_info 0
		.amdhsa_system_vgpr_workitem_id 0
		.amdhsa_next_free_vgpr 256
		.amdhsa_next_free_sgpr 100
		.amdhsa_accum_offset 256
		.amdhsa_reserve_vcc 1
		.amdhsa_float_round_mode_32 0
		.amdhsa_float_round_mode_16_64 0
		.amdhsa_float_denorm_mode_32 3
		.amdhsa_float_denorm_mode_16_64 3
		.amdhsa_dx10_clamp 1
		.amdhsa_ieee_mode 1
		.amdhsa_fp16_overflow 0
		.amdhsa_tg_split 0
		.amdhsa_exception_fp_ieee_invalid_op 0
		.amdhsa_exception_fp_denorm_src 0
		.amdhsa_exception_fp_ieee_div_zero 0
		.amdhsa_exception_fp_ieee_overflow 0
		.amdhsa_exception_fp_ieee_underflow 0
		.amdhsa_exception_fp_ieee_inexact 0
		.amdhsa_exception_int_div_zero 0
	.end_amdhsa_kernel

; __global__ void __launch_bounds__(512, 2) mk_fwd(Args args) {
amdhsa.kernels:
  - .agpr_count:     0
    .args:
      - .offset:         0
        .size:           208
        .value_kind:     by_value
      - .offset:         208
        .size:           4
        .value_kind:     hidden_block_count_x
      - .offset:         212
        .size:           4
        .value_kind:     hidden_block_count_y
      - .offset:         216
        .size:           4
        .value_kind:     hidden_block_count_z
      - .offset:         220
        .size:           2
        .value_kind:     hidden_group_size_x
      - .offset:         222
        .size:           2
        .value_kind:     hidden_group_size_y
      - .offset:         224
        .size:           2
        .value_kind:     hidden_group_size_z
      - .offset:         226
        .size:           2
        .value_kind:     hidden_remainder_x
      - .offset:         228
        .size:           2
        .value_kind:     hidden_remainder_y
      - .offset:         230
        .size:           2
        .value_kind:     hidden_remainder_z
      - .offset:         248
        .size:           8
        .value_kind:     hidden_global_offset_x
      - .offset:         256
        .size:           8
        .value_kind:     hidden_global_offset_y
      - .offset:         264
        .size:           8
        .value_kind:     hidden_global_offset_z
      - .offset:         272
        .size:           2
        .value_kind:     hidden_grid_dims
      - .offset:         328
        .size:           4
        .value_kind:     hidden_dynamic_lds_size
    .group_segment_fixed_size: 0
    .kernarg_segment_align: 8
    .kernarg_segment_size: 464
    .language:       OpenCL C
    .language_version:
      - 2
      - 0
    .max_flat_workgroup_size: 512
    .name:           _Z6mk_fwd4Args
    .private_segment_fixed_size: 0
    .sgpr_count:     106
    .sgpr_spill_count: 53
    .symbol:         _Z6mk_fwd4Args.kd
    .uniform_work_group_size: 1
    .uses_dynamic_stack: false
    .vgpr_count:     256
    .vgpr_spill_count: 0
    .wavefront_size: 64
